# cross-attention: running softmax reference moves only on jumps above 8 (log2 units), so the accumulator rescale runs on the first tile and on large jumps only
# baseline (speedup 1.0000x reference)
.Lxa_tile:
	s_waitcnt lgkmcnt(7)
	v_mfma_f32_32x32x16_bf16 v[66:81], v[114:117], v[82:85], 0
	ds_read_b128 v[146:149], v181
	s_waitcnt lgkmcnt(7)
	v_mfma_f32_32x32x16_bf16 v[66:81], v[118:121], v[86:89], v[66:81]
	ds_read_b128 v[162:165], v181 offset:1024
	s_waitcnt lgkmcnt(7)
	v_mfma_f32_32x32x16_bf16 v[66:81], v[122:125], v[90:93], v[66:81]
	ds_read_b128 v[150:153], v181 offset:2048
	s_waitcnt lgkmcnt(7)
	v_mfma_f32_32x32x16_bf16 v[66:81], v[126:129], v[94:97], v[66:81]
	ds_read_b128 v[166:169], v181 offset:3072
	s_waitcnt lgkmcnt(7)
	v_mfma_f32_32x32x16_bf16 v[66:81], v[130:133], v[98:101], v[66:81]
	ds_read_b128 v[154:157], v181 offset:4096
	s_waitcnt lgkmcnt(7)
	v_mfma_f32_32x32x16_bf16 v[66:81], v[134:137], v[102:105], v[66:81]
	ds_read_b128 v[170:173], v181 offset:5120
	s_waitcnt lgkmcnt(7)
	v_mfma_f32_32x32x16_bf16 v[66:81], v[138:141], v[106:109], v[66:81]
	ds_read_b128 v[158:161], v181 offset:6144
	s_waitcnt lgkmcnt(7)
	v_mfma_f32_32x32x16_bf16 v[66:81], v[142:145], v[110:113], v[66:81]
	ds_read_b128 v[174:177], v181 offset:7168
	s_nop 11
	v_max3_f32 v212, v66, v67, v68
	v_max3_f32 v213, v69, v70, v71
	v_max3_f32 v220, v72, v73, v74
	v_max3_f32 v221, v75, v76, v77
	v_max3_f32 v238, v78, v79, v80
	v_max3_f32 v212, v212, v213, v220
	v_max3_f32 v221, v221, v238, v81
	v_max_f32_e32 v212, v212, v221
	ds_bpermute_b32 v213, v247, v212
	v_add_u32_e32 v180, 0x2000, v180
	s_waitcnt lgkmcnt(0)
	ds_read_b128 v[114:117], v180
	ds_read_b128 v[118:121], v180 offset:1024
	ds_read_b128 v[122:125], v180 offset:2048
	ds_read_b128 v[126:129], v180 offset:3072
	ds_read_b128 v[130:133], v180 offset:4096
	ds_read_b128 v[134:137], v180 offset:5120
	ds_read_b128 v[138:141], v180 offset:6144
	ds_read_b128 v[142:145], v180 offset:7168
	v_med3_f32 v212, v212, v213, s89
	v_mul_f32_e32 v212, 0x3e0293ee, v212
	v_max_f32_e32 v213, v248, v248
	v_add_f32_e32 v220, 0x41000000, v213
	v_cmp_gt_f32_e32 vcc, v212, v220
	s_nop 1
	v_cndmask_b32_e32 v220, v213, v212, vcc
	v_fma_f32 v66, v66, s67, -v220
	v_fma_f32 v67, v67, s67, -v220
	v_fma_f32 v68, v68, s67, -v220
	v_fma_f32 v69, v69, s67, -v220
	v_fma_f32 v70, v70, s67, -v220
	v_fma_f32 v71, v71, s67, -v220
	v_fma_f32 v72, v72, s67, -v220
	v_fma_f32 v73, v73, s67, -v220
	v_fma_f32 v74, v74, s67, -v220
	v_fma_f32 v75, v75, s67, -v220
	v_fma_f32 v76, v76, s67, -v220
	v_fma_f32 v77, v77, s67, -v220
	v_fma_f32 v78, v78, s67, -v220
	v_fma_f32 v79, v79, s67, -v220
	v_fma_f32 v80, v80, s67, -v220
	v_fma_f32 v81, v81, s67, -v220
	v_exp_f32_e32 v66, v66
	v_exp_f32_e32 v67, v67
	v_add_f32_e32 v221, 0, v66
	v_exp_f32_e32 v68, v68
	v_add_f32_e32 v221, v67, v221
	v_exp_f32_e32 v69, v69
	v_add_f32_e32 v221, v68, v221
	v_exp_f32_e32 v70, v70
	v_add_f32_e32 v221, v69, v221
	v_exp_f32_e32 v71, v71
	v_add_f32_e32 v221, v70, v221
	v_exp_f32_e32 v72, v72
	v_add_f32_e32 v221, v71, v221
	v_exp_f32_e32 v73, v73
	v_add_f32_e32 v221, v72, v221
	v_exp_f32_e32 v74, v74
	v_add_f32_e32 v221, v73, v221
	v_exp_f32_e32 v75, v75
	v_add_f32_e32 v221, v74, v221
	v_exp_f32_e32 v76, v76
	v_add_f32_e32 v221, v75, v221
	v_exp_f32_e32 v77, v77
	v_add_f32_e32 v221, v76, v221
	v_exp_f32_e32 v78, v78
	v_add_f32_e32 v221, v77, v221
	v_exp_f32_e32 v79, v79
	v_add_f32_e32 v221, v78, v221
	v_exp_f32_e32 v80, v80
	v_add_f32_e32 v221, v79, v221
	v_exp_f32_e32 v81, v81
	v_add_f32_e32 v221, v80, v221
	v_sub_f32_e32 v213, v248, v220
	v_add_f32_e32 v221, v81, v221
	v_exp_f32_e32 v236, v213
	v_mov_b32_e32 v248, v220
	ds_bpermute_b32 v238, v247, v221
	v_cmp_neq_f32_e32 vcc, 1.0, v236
	s_cbranch_vccz .Lxa_noresc
	v_pk_mul_f32 v[64:65], v[64:65], v[236:237] op_sel_hi:[1,0]
	v_pk_mul_f32 v[62:63], v[62:63], v[236:237] op_sel_hi:[1,0]
	v_pk_mul_f32 v[60:61], v[60:61], v[236:237] op_sel_hi:[1,0]
	v_pk_mul_f32 v[58:59], v[58:59], v[236:237] op_sel_hi:[1,0]
	v_pk_mul_f32 v[56:57], v[56:57], v[236:237] op_sel_hi:[1,0]
	v_pk_mul_f32 v[54:55], v[54:55], v[236:237] op_sel_hi:[1,0]
	v_pk_mul_f32 v[52:53], v[52:53], v[236:237] op_sel_hi:[1,0]
	v_pk_mul_f32 v[50:51], v[50:51], v[236:237] op_sel_hi:[1,0]
	v_pk_mul_f32 v[48:49], v[48:49], v[236:237] op_sel_hi:[1,0]
	v_pk_mul_f32 v[46:47], v[46:47], v[236:237] op_sel_hi:[1,0]
	v_pk_mul_f32 v[44:45], v[44:45], v[236:237] op_sel_hi:[1,0]
	v_pk_mul_f32 v[42:43], v[42:43], v[236:237] op_sel_hi:[1,0]
	v_pk_mul_f32 v[40:41], v[40:41], v[236:237] op_sel_hi:[1,0]
	v_pk_mul_f32 v[38:39], v[38:39], v[236:237] op_sel_hi:[1,0]
	v_pk_mul_f32 v[36:37], v[36:37], v[236:237] op_sel_hi:[1,0]
	v_pk_mul_f32 v[34:35], v[34:35], v[236:237] op_sel_hi:[1,0]
	v_pk_mul_f32 v[32:33], v[32:33], v[236:237] op_sel_hi:[1,0]
	v_pk_mul_f32 v[30:31], v[30:31], v[236:237] op_sel_hi:[1,0]
	v_pk_mul_f32 v[28:29], v[28:29], v[236:237] op_sel_hi:[1,0]
	v_pk_mul_f32 v[26:27], v[26:27], v[236:237] op_sel_hi:[1,0]
	v_pk_mul_f32 v[24:25], v[24:25], v[236:237] op_sel_hi:[1,0]
	v_pk_mul_f32 v[22:23], v[22:23], v[236:237] op_sel_hi:[1,0]
	v_pk_mul_f32 v[20:21], v[20:21], v[236:237] op_sel_hi:[1,0]
	v_pk_mul_f32 v[18:19], v[18:19], v[236:237] op_sel_hi:[1,0]
	v_pk_mul_f32 v[16:17], v[16:17], v[236:237] op_sel_hi:[1,0]
	v_pk_mul_f32 v[14:15], v[14:15], v[236:237] op_sel_hi:[1,0]
	v_pk_mul_f32 v[12:13], v[12:13], v[236:237] op_sel_hi:[1,0]
	v_pk_mul_f32 v[10:11], v[10:11], v[236:237] op_sel_hi:[1,0]
	v_pk_mul_f32 v[8:9], v[8:9], v[236:237] op_sel_hi:[1,0]
	v_pk_mul_f32 v[6:7], v[6:7], v[236:237] op_sel_hi:[1,0]
	v_pk_mul_f32 v[4:5], v[4:5], v[236:237] op_sel_hi:[1,0]
	v_pk_mul_f32 v[2:3], v[2:3], v[236:237] op_sel_hi:[1,0]
